# combined: VT-epilogue load batching, relaxed store drain at dil GEMM job exits, scan LDS/MFMA pipelining, no entry grid.sync
# speedup vs baseline: 1.0038x; 1.0012x over previous
.LBB0_534:
	s_waitcnt vmcnt(16)
	v_readlane_b32 s44, v253, 49
	v_readlane_b32 s46, v253, 47
	v_readlane_b32 s45, v253, 50
	v_readlane_b32 s80, v253, 53
	v_readlane_b32 s47, v253, 48
	v_readlane_b32 s81, v253, 54
	v_readlane_b32 s45, v253, 57
	s_mov_b32 s95, s65
	s_movk_i32 s77, 0x100
	s_movk_i32 s94, 0x7fff
	v_readlane_b32 s43, v249, 56
	s_mov_b32 s52, s64
	s_barrier

.LBB0_589:
	s_waitcnt vmcnt(16)
	v_readlane_b32 s44, v253, 49
	v_readlane_b32 s46, v253, 47
	v_readlane_b32 s45, v253, 50
	v_readlane_b32 s80, v253, 53
	v_readlane_b32 s47, v253, 48
	v_readlane_b32 s81, v253, 54
	v_readlane_b32 s45, v253, 57
	s_mov_b32 s95, s11
	s_movk_i32 s77, 0x100
	s_movk_i32 s94, 0x7fff
	s_mov_b32 s52, s66
	s_barrier
